# v74 + attention work-queue ticket prefetch: own-queue atomic issued at the start of the masked tiles, consumed in the unit epilogue
# speedup vs baseline: 1.0073x; 1.0070x over previous
; __device__ __forceinline__ unsigned xb_xcc_id() { return (unsigned)__builtin_amdgcn_s_getreg((3 << 11) | 20) & 0xFu; }
; #define A_FETCH(res) do { res = 0xffffffffu; \
;             for (unsigned i_ = 0; i_ < 8u && res == 0xffffffffu; ++i_) { const unsigned j_ = (xcc + i_) & 7u; \
;                 if (dead & (1u << j_)) continue; \
;                 const unsigned k_ = atomicAdd(a.ctr + 32 * j_, 1u); \
;                 if (k_ < 2u * NQB) res = (j_ << 8) | k_; else dead |= 1u << j_; } } while (0)
; __device__ __forceinline__ void attn_phase(LAS unsigned char* lds, const AttnArgs& a, int tid_in) {
;     ...
;     const unsigned xcc = xb_xcc_id() & 7u;
;     unsigned dead = 0u;
;     ...
;     bf16x8 qr[4]; const bf16_t* kg; u32x4 kreg[2], vreg[2];
;     int qb, b, h, NT; size_t rowb;
;     {
;         if (tid == 0) { unsigned res; A_FETCH(res); *sU = res; }
; __global__ void __launch_bounds__(512) hymba_fwd(Params p) {
;     ...
;             float d1 = 0.f, d2 = 0.f, mq = 0.f, mk = 0.f;
;             for (int j = 0; j < 64; ++j) { d1 += p.in[6][l * 64 + j] * p.in[7][l * 64 + j]; d2 += p.in[8][l * 64 + j] * p.in[9][l * 64 + j];
;                 mq = fmaxf(mq, fabsf(p.in[4][l * 64 + j])); mk = fmaxf(mk, fabsf(p.in[5][l * 64 + j])); }
;             AttnArgs aa{PJ, MIX, p.in[10] + l * 128, (unsigned*)(ws + WS_CTL) + 512 * l, __expf(d1) - __expf(d2) + lam_init, 8.0f * 1.4426950408889634f * mq * mk, 1.0f - lam_init};
.LBB0_559:
	v_and_b32_e32 v6, 63, v212
	v_lshlrev_b32_e32 v6, 2, v6
	global_load_dword v7, v6, s[2:3]
	s_mov_b32 s30, s6
	s_mov_b32 s31, s10
	global_load_dword v8, v6, s[30:31]
	s_mov_b32 s30, s11
	s_mov_b32 s31, s14
	global_load_dword v9, v6, s[30:31]
	s_mov_b32 s30, s15
	s_mov_b32 s31, s20
	global_load_dword v10, v6, s[30:31]
	global_load_dword v11, v6, s[58:59]
	global_load_dword v12, v6, s[60:61]
	s_waitcnt vmcnt(0)
	v_mul_f32_e32 v2, v7, v8
	v_mul_f32_e32 v3, v9, v10
	v_and_b32_e32 v5, 0x7fffffff, v11
	v_and_b32_e32 v4, 0x7fffffff, v12
	s_nop 1
	v_add_f32_dpp v2, v2, v2 quad_perm:[1,0,3,2] row_mask:0xf bank_mask:0xf
	v_add_f32_dpp v3, v3, v3 quad_perm:[1,0,3,2] row_mask:0xf bank_mask:0xf
	v_max_f32_dpp v5, v5, v5 quad_perm:[1,0,3,2] row_mask:0xf bank_mask:0xf
	v_max_f32_dpp v4, v4, v4 quad_perm:[1,0,3,2] row_mask:0xf bank_mask:0xf
	v_add_f32_dpp v2, v2, v2 quad_perm:[2,3,0,1] row_mask:0xf bank_mask:0xf
	v_add_f32_dpp v3, v3, v3 quad_perm:[2,3,0,1] row_mask:0xf bank_mask:0xf
	v_max_f32_dpp v5, v5, v5 quad_perm:[2,3,0,1] row_mask:0xf bank_mask:0xf
	v_max_f32_dpp v4, v4, v4 quad_perm:[2,3,0,1] row_mask:0xf bank_mask:0xf
	v_add_f32_dpp v2, v2, v2 row_half_mirror row_mask:0xf bank_mask:0xf
	v_add_f32_dpp v3, v3, v3 row_half_mirror row_mask:0xf bank_mask:0xf
	v_max_f32_dpp v5, v5, v5 row_half_mirror row_mask:0xf bank_mask:0xf
	v_max_f32_dpp v4, v4, v4 row_half_mirror row_mask:0xf bank_mask:0xf
	v_add_f32_dpp v2, v2, v2 row_mirror row_mask:0xf bank_mask:0xf
	v_add_f32_dpp v3, v3, v3 row_mirror row_mask:0xf bank_mask:0xf
	v_max_f32_dpp v5, v5, v5 row_mirror row_mask:0xf bank_mask:0xf
	v_max_f32_dpp v4, v4, v4 row_mirror row_mask:0xf bank_mask:0xf
	s_nop 1
	v_readlane_b32 s6, v2, 0
	v_readlane_b32 s10, v2, 16
	v_readlane_b32 s11, v2, 32
	v_readlane_b32 s14, v2, 48
	s_nop 1
	v_mov_b32_e32 v2, s6
	v_add_f32_e32 v2, s10, v2
	v_add_f32_e32 v2, s11, v2
	v_add_f32_e32 v2, s14, v2
	v_readlane_b32 s6, v3, 0
	v_readlane_b32 s10, v3, 16
	v_readlane_b32 s11, v3, 32
	v_readlane_b32 s14, v3, 48
	s_nop 1
	v_mov_b32_e32 v3, s6
	v_add_f32_e32 v3, s10, v3
	v_add_f32_e32 v3, s11, v3
	v_add_f32_e32 v3, s14, v3
	v_readlane_b32 s6, v5, 0
	v_readlane_b32 s10, v5, 16
	v_readlane_b32 s11, v5, 32
	v_readlane_b32 s14, v5, 48
	s_nop 1
	v_mov_b32_e32 v5, s6
	v_max_f32_e32 v5, s10, v5
	v_max_f32_e32 v5, s11, v5
	v_max_f32_e32 v5, s14, v5
	v_readlane_b32 s6, v4, 0
	v_readlane_b32 s10, v4, 16
	v_readlane_b32 s11, v4, 32
	v_readlane_b32 s14, v4, 48
	s_nop 1
	v_mov_b32_e32 v4, s6
	v_max_f32_e32 v4, s10, v4
	v_max_f32_e32 v4, s11, v4
	v_max_f32_e32 v4, s14, v4
	s_add_u32 s8, s24, s40
	v_mov_b32_e32 v193, v212
	s_addc_u32 s9, s25, s41
	s_getreg_b32 s2, hwreg(HW_REG_XCC_ID, 0, 4)
	v_readfirstlane_b32 s30, v193
	v_mov_b32_e32 v221, 0
	v_cmp_eq_u32_e64 s[36:37], 0, v193
	s_mov_b32 s98, 0
	s_and_saveexec_b64 s[10:11], s[36:37]
	s_cbranch_execz .LBB0_568
	v_mov_b32_e32 v221, 0
	s_mov_b64 s[14:15], 0
	s_mov_b32 s3, 0
	s_branch .LBB0_564

; #define A_LOAD(t) do { _Pragma("unroll") for (int j_ = 0; j_ < 2; ++j_) { kreg[j_] = *(const u32x4*)(kg + (size_t)(64 * (t) + 32 * j_) * NIN); vreg[j_] = *(const u32x4*)(kg + 512 + (size_t)(64 * (t) + 32 * j_) * NIN); } } while (0)
; #define A_STORE(kbi, vbi) do { _Pragma("unroll") for (int j_ = 0; j_ < 2; ++j_) { *(LAS u32x4*)(lds + A_K0 + (kbi) * KBUF + (skey + 32 * j_) * KSTR + sch * 16) = kreg[j_]; *(LAS u32x4*)(lds + A_V0 + (vbi) * VBUF + (skey + 32 * j_) * VSTR + sch * 16) = vreg[j_]; } } while (0)
; __device__ __forceinline__ void attn_phase(LAS unsigned char* lds, const AttnArgs& a, int tid_in) {
;     ...
;         for (; t < NT; ++t) {
;             A_PIPE(true, t, vp);
;             if (t + 1 < NT) A_STORE((t + 1) & 1, vn);
;             if (t + 2 < NT) A_LOAD(t + 2);
.LBB0_584:
	s_mov_b32 s98, 0
	s_and_saveexec_b64 s[100:101], s[36:37]
	s_cbranch_execz .Ltk_pf_end
	v_readfirstlane_b32 s99, v221
	s_and_b32 s98, s2, 7
	s_lshr_b32 s99, s99, s98
	s_and_b32 s99, s99, 1
	s_lshl_b32 s98, s98, 7
	v_mov_b32_e32 v23, s98
	s_mov_b32 s98, 0
	s_cmp_eq_u32 s99, 0
	s_cbranch_scc0 .Ltk_pf_end
	v_mov_b32_e32 v22, 1
	global_atomic_add v23, v23, v22, s[8:9] sc0
	s_mov_b32 s98, 1
.Ltk_pf_end:
	s_or_b64 exec, exec, s[100:101]
	s_cmp_ge_i32 s35, s27
	s_cbranch_scc1 .LBB0_591
	v_lshl_add_u32 v0, s3, 7, v233
	s_lshl_b32 s4, s35, 6
	v_subrev_u32_e32 v0, s4, v0
	s_add_i32 s30, s4, 0xa0
	s_add_i32 s31, s35, 2
	v_mov_b32_e32 v2, v211
	s_branch .LBB0_587

; #define A_FETCH(res) do { res = 0xffffffffu; \
;             for (unsigned i_ = 0; i_ < 8u && res == 0xffffffffu; ++i_) { const unsigned j_ = (xcc + i_) & 7u; \
;                 if (dead & (1u << j_)) continue; \
;                 const unsigned k_ = atomicAdd(a.ctr + 32 * j_, 1u); \
;                 if (k_ < 2u * NQB) res = (j_ << 8) | k_; else dead |= 1u << j_; } } while (0)
; __device__ __forceinline__ void attn_phase(LAS unsigned char* lds, const AttnArgs& a, int tid_in) {
;     ...
;         if (tid == 0) { unsigned res; A_FETCH(res); *sU = res; }
.LBB0_598:
	s_add_i32 s27, s2, s6
	s_and_b32 s30, s27, 7
	s_lshl_b32 s27, 1, s30
	v_and_b32_e32 v0, s27, v221
	v_cmp_eq_u32_e32 vcc, 0, v0
	v_mov_b32_e32 v0, -1
	s_and_saveexec_b64 s[42:43], vcc
	s_cbranch_execz .LBB0_597
	s_mov_b64 s[46:47], exec
	v_mbcnt_lo_u32_b32 v0, s46, 0
	v_mbcnt_hi_u32_b32 v0, s47, v0
	v_cmp_eq_u32_e32 vcc, 0, v0
	s_and_saveexec_b64 s[44:45], vcc
	s_cbranch_execz .LBB0_596
	s_cmp_eq_u32 s98, 1
	s_cbranch_scc1 .Ltk_use_pf
	s_lshl_b32 s31, s30, 7
	s_bcnt1_i32_b64 s34, s[46:47]
	v_mov_b32_e32 v14, s31
	v_mov_b32_e32 v15, s34
	global_atomic_add v14, v14, v15, s[8:9] sc0
	s_branch .LBB0_596
.Ltk_use_pf:
	s_mov_b32 s98, 0
	s_waitcnt vmcnt(0)
	v_mov_b32_e32 v14, v23
	s_branch .LBB0_596

; __global__ void __launch_bounds__(512) hymba_fwd(Params p) {
	.amdhsa_kernel _Z9hymba_fwd6Params
		.amdhsa_group_segment_fixed_size 0
		.amdhsa_private_segment_fixed_size 0
		.amdhsa_kernarg_size 456
		.amdhsa_user_sgpr_count 2
		.amdhsa_user_sgpr_dispatch_ptr 0
		.amdhsa_user_sgpr_queue_ptr 0
		.amdhsa_user_sgpr_kernarg_segment_ptr 1
		.amdhsa_user_sgpr_dispatch_id 0
		.amdhsa_user_sgpr_kernarg_preload_length 0
		.amdhsa_user_sgpr_kernarg_preload_offset 0
		.amdhsa_user_sgpr_private_segment_size 0
		.amdhsa_uses_dynamic_stack 0
		.amdhsa_enable_private_segment 0
		.amdhsa_system_sgpr_workgroup_id_x 1
		.amdhsa_system_sgpr_workgroup_id_y 0
		.amdhsa_system_sgpr_workgroup_id_z 0
		.amdhsa_system_sgpr_workgroup_info 0
		.amdhsa_system_vgpr_workitem_id 2
		.amdhsa_next_free_vgpr 256
		.amdhsa_next_free_sgpr 102
		.amdhsa_accum_offset 256
		.amdhsa_reserve_vcc 1
		.amdhsa_float_round_mode_32 0
		.amdhsa_float_round_mode_16_64 0
		.amdhsa_float_denorm_mode_32 3
		.amdhsa_float_denorm_mode_16_64 3
		.amdhsa_dx10_clamp 1
		.amdhsa_ieee_mode 1
		.amdhsa_fp16_overflow 0
		.amdhsa_tg_split 0
		.amdhsa_exception_fp_ieee_invalid_op 0
		.amdhsa_exception_fp_denorm_src 0
		.amdhsa_exception_fp_ieee_div_zero 0
		.amdhsa_exception_fp_ieee_overflow 0
		.amdhsa_exception_fp_ieee_underflow 0
		.amdhsa_exception_fp_ieee_inexact 0
		.amdhsa_exception_int_div_zero 0
	.end_amdhsa_kernel

; __global__ void __launch_bounds__(512) hymba_fwd(Params p) {
amdhsa.kernels:
  - .agpr_count:     0
    .args:
      - .offset:         0
        .size:           200
        .value_kind:     by_value
      - .offset:         200
        .size:           4
        .value_kind:     hidden_block_count_x
      - .offset:         204
        .size:           4
        .value_kind:     hidden_block_count_y
      - .offset:         208
        .size:           4
        .value_kind:     hidden_block_count_z
      - .offset:         212
        .size:           2
        .value_kind:     hidden_group_size_x
      - .offset:         214
        .size:           2
        .value_kind:     hidden_group_size_y
      - .offset:         216
        .size:           2
        .value_kind:     hidden_group_size_z
      - .offset:         218
        .size:           2
        .value_kind:     hidden_remainder_x
      - .offset:         220
        .size:           2
        .value_kind:     hidden_remainder_y
      - .offset:         222
        .size:           2
        .value_kind:     hidden_remainder_z
      - .offset:         240
        .size:           8
        .value_kind:     hidden_global_offset_x
      - .offset:         248
        .size:           8
        .value_kind:     hidden_global_offset_y
      - .offset:         256
        .size:           8
        .value_kind:     hidden_global_offset_z
      - .offset:         264
        .size:           2
        .value_kind:     hidden_grid_dims
      - .offset:         288
        .size:           8
        .value_kind:     hidden_multigrid_sync_arg
      - .offset:         320
        .size:           4
        .value_kind:     hidden_dynamic_lds_size
    .group_segment_fixed_size: 0
    .kernarg_segment_align: 8
    .kernarg_segment_size: 456
    .language:       OpenCL C
    .language_version:
      - 2
      - 0
    .max_flat_workgroup_size: 512
    .name:           _Z9hymba_fwd6Params
    .private_segment_fixed_size: 0
    .sgpr_count:     108
    .sgpr_spill_count: 198
    .symbol:         _Z9hymba_fwd6Params.kd
    .uniform_work_group_size: 1
    .uses_dynamic_stack: false
    .vgpr_count:     256
    .vgpr_spill_count: 0
    .wavefront_size: 64
